# sgu prompt unit output stage: the 4 bias loads issued together, per-group vmcnt(0) round trips replaced by counted waits that leave the stores in flight
# baseline (speedup 1.0000x reference)
.LBB0_663:
	v_or_b32_e32 v0, s7, v172
	s_add_i32 s0, s8, s43
	v_or_b32_e32 v62, s0, v0
	v_ashrrev_i32_e32 v63, 31, v62
	v_lshl_add_u64 v[62:63], v[62:63], 2, s[66:67]
	global_load_dword v65, v[62:63], off
	global_load_dword v244, v[62:63], off offset:64
	global_load_dword v245, v[62:63], off offset:128
	global_load_dword v246, v[62:63], off offset:192
	s_waitcnt vmcnt(19)
	v_lshlrev_b32_e32 v70, 16, v154
	v_and_b32_e32 v71, 0xffff0000, v154
	v_ashrrev_i32_e32 v171, 31, v170
	v_readlane_b32 s6, v254, 20
	v_lshlrev_b64 v[62:63], 11, v[170:171]
	v_readlane_b32 s7, v254, 21
	s_ashr_i32 s1, s0, 31
	v_ashrrev_i32_e32 v169, 31, v168
	v_lshl_add_u64 v[62:63], s[6:7], 0, v[62:63]
	v_ashrrev_i32_e32 v167, 31, v166
	v_ashrrev_i32_e32 v165, 31, v164
	s_add_i32 s10, s10, s78
	s_waitcnt vmcnt(3)
	v_add_f32_e32 v64, v158, v65
	v_mul_f32_e32 v64, v64, v70
	v_lshlrev_b32_e32 v70, 16, v150
	v_mul_f32_e32 v64, v64, v70
	v_add_f32_e32 v70, v159, v65
	v_mul_f32_e32 v70, v70, v71
	v_and_b32_e32 v71, 0xffff0000, v150
	v_mul_f32_e32 v70, v70, v71
	v_cvt_pk_bf16_f32 v72, v64, v70
	v_add_f32_e32 v64, v160, v65
	v_lshlrev_b32_e32 v70, 16, v155
	v_mul_f32_e32 v64, v64, v70
	v_lshlrev_b32_e32 v70, 16, v151
	v_mul_f32_e32 v64, v64, v70
	v_add_f32_e32 v70, v161, v65
	v_and_b32_e32 v71, 0xffff0000, v155
	v_mul_f32_e32 v70, v70, v71
	v_and_b32_e32 v71, 0xffff0000, v151
	v_mul_f32_e32 v70, v70, v71
	v_cvt_pk_bf16_f32 v73, v64, v70
	v_add_f32_e32 v64, v146, v65
	v_lshlrev_b32_e32 v70, 16, v156
	v_mul_f32_e32 v64, v64, v70
	v_lshlrev_b32_e32 v70, 16, v152
	v_mul_f32_e32 v64, v64, v70
	v_add_f32_e32 v70, v147, v65
	v_and_b32_e32 v71, 0xffff0000, v156
	v_mul_f32_e32 v70, v70, v71
	v_and_b32_e32 v71, 0xffff0000, v152
	v_mul_f32_e32 v70, v70, v71
	v_cvt_pk_bf16_f32 v74, v64, v70
	v_add_f32_e32 v64, v148, v65
	v_lshlrev_b32_e32 v70, 16, v157
	v_mul_f32_e32 v64, v64, v70
	v_lshlrev_b32_e32 v70, 16, v153
	v_mul_f32_e32 v64, v64, v70
	v_add_f32_e32 v70, v149, v65
	v_and_b32_e32 v71, 0xffff0000, v157
	v_mul_f32_e32 v70, v70, v71
	v_and_b32_e32 v71, 0xffff0000, v153
	v_mul_f32_e32 v70, v70, v71
	v_cvt_pk_bf16_f32 v75, v64, v70
	v_lshl_add_u64 v[70:71], v[62:63], 0, v[162:163]
	v_add_f32_e32 v62, v142, v65
	v_lshlrev_b32_e32 v63, 16, v134
	v_mul_f32_e32 v62, v62, v63
	v_lshlrev_b32_e32 v63, 16, v138
	v_mul_f32_e32 v62, v62, v63
	v_add_f32_e32 v63, v143, v65
	v_and_b32_e32 v64, 0xffff0000, v134
	v_mul_f32_e32 v63, v63, v64
	v_and_b32_e32 v64, 0xffff0000, v138
	v_mul_f32_e32 v63, v63, v64
	global_store_dwordx4 v[70:71], v[72:75], off
	v_cvt_pk_bf16_f32 v62, v62, v63
	v_add_f32_e32 v63, v144, v65
	v_lshlrev_b32_e32 v64, 16, v135
	v_mul_f32_e32 v63, v63, v64
	v_lshlrev_b32_e32 v64, 16, v139
	v_mul_f32_e32 v63, v63, v64
	v_add_f32_e32 v64, v145, v65
	v_and_b32_e32 v72, 0xffff0000, v135
	v_mul_f32_e32 v64, v64, v72
	v_and_b32_e32 v72, 0xffff0000, v139
	v_mul_f32_e32 v64, v64, v72
	v_cvt_pk_bf16_f32 v63, v63, v64
	v_add_f32_e32 v64, v130, v65
	v_lshlrev_b32_e32 v72, 16, v136
	v_mul_f32_e32 v64, v64, v72
	v_lshlrev_b32_e32 v72, 16, v140
	v_mul_f32_e32 v64, v64, v72
	v_add_f32_e32 v72, v131, v65
	v_and_b32_e32 v73, 0xffff0000, v136
	v_mul_f32_e32 v72, v72, v73
	v_and_b32_e32 v73, 0xffff0000, v140
	v_mul_f32_e32 v72, v72, v73
	v_cvt_pk_bf16_f32 v64, v64, v72
	v_add_f32_e32 v72, v132, v65
	v_lshlrev_b32_e32 v73, 16, v137
	v_mul_f32_e32 v72, v72, v73
	v_lshlrev_b32_e32 v73, 16, v141
	v_mul_f32_e32 v72, v72, v73
	v_add_f32_e32 v65, v133, v65
	v_and_b32_e32 v73, 0xffff0000, v137
	v_mul_f32_e32 v65, v65, v73
	v_and_b32_e32 v73, 0xffff0000, v141
	v_mul_f32_e32 v65, v65, v73
	v_cvt_pk_bf16_f32 v65, v72, v65
	global_store_dwordx4 v[70:71], v[62:65], off offset:64
	v_lshlrev_b32_e32 v71, 16, v122
	v_and_b32_e32 v72, 0xffff0000, v122
	v_lshl_add_u64 v[62:63], v[0:1], 0, s[0:1]
	v_lshl_add_u64 v[62:63], v[62:63], 2, s[66:67]
	s_nop 0
	v_and_b32_e32 v73, 0xffff0000, v123
	v_and_b32_e32 v74, 0xffff0000, v124
	v_lshlrev_b64 v[64:65], 11, v[168:169]
	v_lshl_add_u64 v[64:65], s[6:7], 0, v[64:65]
	v_and_b32_e32 v75, 0xffff0000, v125
	v_lshl_add_u64 v[64:65], v[64:65], 0, v[162:163]
	s_cmp_eq_u32 s100, 0xffffffff
	s_cbranch_scc0 .Lsgu_nx
	s_movk_i32 s10, 0x400
.Lsgu_nx:
	s_lshl_b32 s0, s10, 7
	s_add_i32 s11, s0, 0xffff0000
	s_cmpk_lt_i32 s10, 0x400
	s_waitcnt vmcnt(4)
	v_mov_b32_e32 v0, v244
	v_add_f32_e32 v70, v126, v0
	v_mul_f32_e32 v70, v70, v71
	v_lshlrev_b32_e32 v71, 16, v118
	v_mul_f32_e32 v70, v70, v71
	v_add_f32_e32 v71, v127, v0
	v_mul_f32_e32 v71, v71, v72
	v_and_b32_e32 v72, 0xffff0000, v118
	v_mul_f32_e32 v71, v71, v72
	v_cvt_pk_bf16_f32 v70, v70, v71
	v_add_f32_e32 v71, v128, v0
	v_lshlrev_b32_e32 v72, 16, v123
	v_mul_f32_e32 v71, v71, v72
	v_lshlrev_b32_e32 v72, 16, v119
	v_mul_f32_e32 v71, v71, v72
	v_add_f32_e32 v72, v129, v0
	v_mul_f32_e32 v72, v72, v73
	v_and_b32_e32 v73, 0xffff0000, v119
	v_mul_f32_e32 v72, v72, v73
	v_cvt_pk_bf16_f32 v71, v71, v72
	v_add_f32_e32 v72, v114, v0
	v_lshlrev_b32_e32 v73, 16, v124
	v_mul_f32_e32 v72, v72, v73
	v_lshlrev_b32_e32 v73, 16, v120
	v_mul_f32_e32 v72, v72, v73
	v_add_f32_e32 v73, v115, v0
	v_mul_f32_e32 v73, v73, v74
	v_and_b32_e32 v74, 0xffff0000, v120
	v_mul_f32_e32 v73, v73, v74
	v_cvt_pk_bf16_f32 v72, v72, v73
	v_add_f32_e32 v73, v116, v0
	v_lshlrev_b32_e32 v74, 16, v125
	v_mul_f32_e32 v73, v73, v74
	v_lshlrev_b32_e32 v74, 16, v121
	v_mul_f32_e32 v73, v73, v74
	v_add_f32_e32 v74, v117, v0
	v_mul_f32_e32 v74, v74, v75
	v_and_b32_e32 v75, 0xffff0000, v121
	v_mul_f32_e32 v74, v74, v75
	v_cvt_pk_bf16_f32 v73, v73, v74
	global_store_dwordx4 v[64:65], v[70:73], off
	v_and_b32_e32 v74, 0xffff0000, v104
	s_nop 0
	v_add_f32_e32 v70, v110, v0
	v_lshlrev_b32_e32 v71, 16, v102
	v_mul_f32_e32 v70, v70, v71
	v_lshlrev_b32_e32 v71, 16, v106
	v_mul_f32_e32 v70, v70, v71
	v_add_f32_e32 v71, v111, v0
	v_and_b32_e32 v72, 0xffff0000, v102
	v_mul_f32_e32 v71, v71, v72
	v_and_b32_e32 v72, 0xffff0000, v106
	v_mul_f32_e32 v71, v71, v72
	v_cvt_pk_bf16_f32 v70, v70, v71
	v_add_f32_e32 v71, v112, v0
	v_lshlrev_b32_e32 v72, 16, v103
	v_mul_f32_e32 v71, v71, v72
	v_lshlrev_b32_e32 v72, 16, v107
	v_mul_f32_e32 v71, v71, v72
	v_add_f32_e32 v72, v113, v0
	v_and_b32_e32 v73, 0xffff0000, v103
	v_mul_f32_e32 v72, v72, v73
	v_and_b32_e32 v73, 0xffff0000, v107
	v_mul_f32_e32 v72, v72, v73
	v_cvt_pk_bf16_f32 v71, v71, v72
	v_add_f32_e32 v72, v98, v0
	v_lshlrev_b32_e32 v73, 16, v104
	v_mul_f32_e32 v72, v72, v73
	v_lshlrev_b32_e32 v73, 16, v108
	v_mul_f32_e32 v72, v72, v73
	v_add_f32_e32 v73, v99, v0
	v_mul_f32_e32 v73, v73, v74
	v_and_b32_e32 v74, 0xffff0000, v108
	v_mul_f32_e32 v73, v73, v74
	v_cvt_pk_bf16_f32 v72, v72, v73
	v_add_f32_e32 v73, v100, v0
	v_lshlrev_b32_e32 v74, 16, v105
	v_mul_f32_e32 v73, v73, v74
	v_lshlrev_b32_e32 v74, 16, v109
	v_mul_f32_e32 v73, v73, v74
	v_add_f32_e32 v0, v101, v0
	v_and_b32_e32 v74, 0xffff0000, v105
	v_mul_f32_e32 v0, v0, v74
	v_and_b32_e32 v74, 0xffff0000, v109
	v_mul_f32_e32 v0, v0, v74
	v_cvt_pk_bf16_f32 v73, v73, v0
	global_store_dwordx4 v[64:65], v[70:73], off offset:64
	s_nop 0
	v_lshlrev_b64 v[64:65], 11, v[166:167]
	v_lshlrev_b32_e32 v70, 16, v58
	v_and_b32_e32 v58, 0xffff0000, v58
	v_lshl_add_u64 v[64:65], s[6:7], 0, v[64:65]
	s_waitcnt vmcnt(5)
	v_mov_b32_e32 v0, v245
	v_add_f32_e32 v66, v66, v0
	v_add_f32_e32 v67, v67, v0
	v_mul_f32_e32 v66, v66, v70
	v_lshlrev_b32_e32 v70, 16, v54
	v_mul_f32_e32 v58, v67, v58
	v_and_b32_e32 v54, 0xffff0000, v54
	v_mul_f32_e32 v66, v66, v70
	v_mul_f32_e32 v54, v58, v54
	v_cvt_pk_bf16_f32 v54, v66, v54
	v_add_f32_e32 v58, v68, v0
	v_lshlrev_b32_e32 v66, 16, v59
	v_mul_f32_e32 v58, v58, v66
	v_lshlrev_b32_e32 v66, 16, v55
	v_mul_f32_e32 v58, v58, v66
	v_add_f32_e32 v66, v69, v0
	v_and_b32_e32 v59, 0xffff0000, v59
	v_mul_f32_e32 v59, v66, v59
	v_and_b32_e32 v55, 0xffff0000, v55
	v_mul_f32_e32 v55, v59, v55
	v_cvt_pk_bf16_f32 v55, v58, v55
	v_add_f32_e32 v50, v50, v0
	v_lshlrev_b32_e32 v58, 16, v60
	v_mul_f32_e32 v50, v50, v58
	v_lshlrev_b32_e32 v58, 16, v56
	v_mul_f32_e32 v50, v50, v58
	v_add_f32_e32 v51, v51, v0
	v_and_b32_e32 v58, 0xffff0000, v60
	v_mul_f32_e32 v51, v51, v58
	v_and_b32_e32 v56, 0xffff0000, v56
	v_mul_f32_e32 v51, v51, v56
	v_cvt_pk_bf16_f32 v56, v50, v51
	v_add_f32_e32 v50, v52, v0
	v_lshlrev_b32_e32 v51, 16, v61
	v_mul_f32_e32 v50, v50, v51
	v_lshlrev_b32_e32 v51, 16, v57
	v_mul_f32_e32 v50, v50, v51
	v_add_f32_e32 v51, v53, v0
	v_and_b32_e32 v52, 0xffff0000, v61
	v_mul_f32_e32 v51, v51, v52
	v_and_b32_e32 v52, 0xffff0000, v57
	v_mul_f32_e32 v51, v51, v52
	v_add_f32_e32 v46, v46, v0
	v_lshlrev_b32_e32 v52, 16, v38
	v_add_f32_e32 v47, v47, v0
	v_and_b32_e32 v38, 0xffff0000, v38
	v_mul_f32_e32 v46, v46, v52
	v_lshlrev_b32_e32 v52, 16, v42
	v_mul_f32_e32 v38, v47, v38
	v_and_b32_e32 v42, 0xffff0000, v42
	v_cvt_pk_bf16_f32 v57, v50, v51
	v_lshl_add_u64 v[50:51], v[64:65], 0, v[162:163]
	v_mul_f32_e32 v46, v46, v52
	v_mul_f32_e32 v38, v38, v42
	global_store_dwordx4 v[50:51], v[54:57], off
	v_cvt_pk_bf16_f32 v38, v46, v38
	v_add_f32_e32 v42, v48, v0
	v_lshlrev_b32_e32 v46, 16, v39
	v_mul_f32_e32 v42, v42, v46
	v_lshlrev_b32_e32 v46, 16, v43
	v_mul_f32_e32 v42, v42, v46
	v_add_f32_e32 v46, v49, v0
	v_and_b32_e32 v39, 0xffff0000, v39
	v_mul_f32_e32 v39, v46, v39
	v_and_b32_e32 v43, 0xffff0000, v43
	v_mul_f32_e32 v39, v39, v43
	v_cvt_pk_bf16_f32 v39, v42, v39
	v_add_f32_e32 v34, v34, v0
	v_lshlrev_b32_e32 v42, 16, v40
	v_add_f32_e32 v35, v35, v0
	v_and_b32_e32 v40, 0xffff0000, v40
	v_mul_f32_e32 v34, v34, v42
	v_lshlrev_b32_e32 v42, 16, v44
	v_mul_f32_e32 v35, v35, v40
	v_and_b32_e32 v40, 0xffff0000, v44
	v_mul_f32_e32 v34, v34, v42
	v_mul_f32_e32 v35, v35, v40
	v_cvt_pk_bf16_f32 v40, v34, v35
	v_add_f32_e32 v34, v36, v0
	v_lshlrev_b32_e32 v35, 16, v41
	v_mul_f32_e32 v34, v34, v35
	v_lshlrev_b32_e32 v35, 16, v45
	v_mul_f32_e32 v34, v34, v35
	v_add_f32_e32 v0, v37, v0
	v_and_b32_e32 v35, 0xffff0000, v41
	v_mul_f32_e32 v0, v0, v35
	v_and_b32_e32 v35, 0xffff0000, v45
	v_mul_f32_e32 v0, v0, v35
	v_cvt_pk_bf16_f32 v41, v34, v0
	global_store_dwordx4 v[50:51], v[38:41], off offset:64
	s_nop 0
	v_lshlrev_b32_e32 v36, 16, v22
	v_and_b32_e32 v22, 0xffff0000, v22
	v_lshlrev_b64 v[34:35], 11, v[164:165]
	v_lshl_add_u64 v[34:35], s[6:7], 0, v[34:35]
	s_waitcnt vmcnt(6)
	v_mov_b32_e32 v0, v246
	v_add_f32_e32 v30, v30, v0
	v_add_f32_e32 v31, v31, v0
	v_mul_f32_e32 v30, v30, v36
	v_lshlrev_b32_e32 v36, 16, v18
	v_mul_f32_e32 v22, v31, v22
	v_and_b32_e32 v18, 0xffff0000, v18
	v_mul_f32_e32 v30, v30, v36
	v_mul_f32_e32 v18, v22, v18
	v_cvt_pk_bf16_f32 v18, v30, v18
	v_add_f32_e32 v22, v32, v0
	v_lshlrev_b32_e32 v30, 16, v23
	v_mul_f32_e32 v22, v22, v30
	v_lshlrev_b32_e32 v30, 16, v19
	v_mul_f32_e32 v22, v22, v30
	v_add_f32_e32 v30, v33, v0
	v_and_b32_e32 v23, 0xffff0000, v23
	v_mul_f32_e32 v23, v30, v23
	v_and_b32_e32 v19, 0xffff0000, v19
	v_mul_f32_e32 v19, v23, v19
	v_cvt_pk_bf16_f32 v19, v22, v19
	v_add_f32_e32 v22, v26, v0
	v_lshlrev_b32_e32 v23, 16, v24
	v_mul_f32_e32 v22, v22, v23
	v_lshlrev_b32_e32 v23, 16, v20
	v_mul_f32_e32 v22, v22, v23
	v_add_f32_e32 v23, v27, v0
	v_and_b32_e32 v24, 0xffff0000, v24
	v_mul_f32_e32 v23, v23, v24
	v_and_b32_e32 v20, 0xffff0000, v20
	v_mul_f32_e32 v20, v23, v20
	v_cvt_pk_bf16_f32 v20, v22, v20
	v_add_f32_e32 v22, v28, v0
	v_lshlrev_b32_e32 v23, 16, v25
	v_mul_f32_e32 v22, v22, v23
	v_lshlrev_b32_e32 v23, 16, v21
	v_mul_f32_e32 v22, v22, v23
	v_add_f32_e32 v23, v29, v0
	v_and_b32_e32 v24, 0xffff0000, v25
	v_mul_f32_e32 v23, v23, v24
	v_and_b32_e32 v21, 0xffff0000, v21
	v_mul_f32_e32 v21, v23, v21
	v_cvt_pk_bf16_f32 v21, v22, v21
	v_lshl_add_u64 v[22:23], v[34:35], 0, v[162:163]
	global_store_dwordx4 v[22:23], v[18:21], off
	v_add_f32_e32 v14, v14, v0
	v_add_f32_e32 v15, v15, v0
	v_lshlrev_b32_e32 v18, 16, v2
	v_and_b32_e32 v2, 0xffff0000, v2
	v_mul_f32_e32 v14, v14, v18
	v_lshlrev_b32_e32 v18, 16, v6
	v_mul_f32_e32 v2, v15, v2
	v_and_b32_e32 v6, 0xffff0000, v6
	v_mul_f32_e32 v14, v14, v18
	v_mul_f32_e32 v2, v2, v6
	v_cvt_pk_bf16_f32 v2, v14, v2
	v_add_f32_e32 v6, v16, v0
	v_lshlrev_b32_e32 v14, 16, v3
	v_mul_f32_e32 v6, v6, v14
	v_lshlrev_b32_e32 v14, 16, v7
	v_mul_f32_e32 v6, v6, v14
	v_add_f32_e32 v14, v17, v0
	v_and_b32_e32 v3, 0xffff0000, v3
	v_mul_f32_e32 v3, v14, v3
	v_and_b32_e32 v7, 0xffff0000, v7
	v_mul_f32_e32 v3, v3, v7
	v_cvt_pk_bf16_f32 v3, v6, v3
	v_add_f32_e32 v6, v10, v0
	v_lshlrev_b32_e32 v7, 16, v4
	v_mul_f32_e32 v6, v6, v7
	v_lshlrev_b32_e32 v7, 16, v8
	v_mul_f32_e32 v6, v6, v7
	v_add_f32_e32 v7, v11, v0
	v_and_b32_e32 v4, 0xffff0000, v4
	v_mul_f32_e32 v4, v7, v4
	v_and_b32_e32 v7, 0xffff0000, v8
	v_mul_f32_e32 v4, v4, v7
	v_cvt_pk_bf16_f32 v4, v6, v4
	v_add_f32_e32 v6, v12, v0
	v_lshlrev_b32_e32 v7, 16, v5
	v_add_f32_e32 v0, v13, v0
	v_and_b32_e32 v5, 0xffff0000, v5
	v_mul_f32_e32 v6, v6, v7
	v_lshlrev_b32_e32 v7, 16, v9
	v_mul_f32_e32 v0, v0, v5
	v_and_b32_e32 v5, 0xffff0000, v9
	v_mul_f32_e32 v6, v6, v7
	v_mul_f32_e32 v0, v0, v5
	v_cvt_pk_bf16_f32 v5, v6, v0
	global_store_dwordx4 v[22:23], v[2:5], off offset:64
	s_barrier
	s_cbranch_scc0 .LBB0_672
